# low-rank K-slice + attention K/V prefetched two groups ahead (loop body duplicated, second dead register set)
# baseline (speedup 1.0000x reference)
.LBB0_620:
	s_bfe_u32 s3, s0, 0x70004
	s_lshl_b32 s6, s3, 8
	s_add_i32 s7, s6, 0x7fffc000
	s_and_b32 s7, s7, 0x7ffff000
	s_and_b32 s10, s0, 15
	s_lshr_b32 s2, s0, 4
	s_ashr_i32 s1, s0, 11
	s_addk_i32 s7, 0x4000
	s_and_b32 s6, s6, 0x2000
	s_cmp_lt_u32 s3, 64
	s_cselect_b32 s3, 31, 15
	s_cselect_b32 s14, 0x2000, s68
	s_cselect_b32 s12, s6, s7
	s_and_b32 s11, s3, s2
	s_lshl_b32 s2, s11, 8
	s_or_b32 s15, s2, s10
	v_or_b32_e32 v110, s15, v102
	v_add_u32_e32 v50, s12, v110
	v_mov_b64_e32 v[0:1], s[4:5]
	v_mad_u64_u32 v[0:1], s[2:3], v50, s31, v[0:1]
	s_lshl_b32 s2, s1, 6
	s_ashr_i32 s3, s2, 31
	s_lshl_b64 s[6:7], s[2:3], 1
	s_mul_hi_u32 s13, s12, 0x900
	s_mulk_i32 s12, 0x900
	s_add_u32 s12, s4, s12
	s_addc_u32 s13, s5, s13
	v_lshl_add_u64 v[0:1], v[0:1], 0, s[6:7]
	s_add_u32 s6, s12, s6
	v_lshl_add_u64 v[0:1], v[96:97], 1, v[0:1]
	s_addc_u32 s7, s13, s7
	s_sub_i32 s12, s15, 64
	global_load_dwordx4 v[16:19], v[0:1], off
	global_load_dwordx4 v[20:23], v[0:1], off offset:64
	v_add_u32_e32 v0, s12, v49
	s_add_i32 s13, s14, -1
	v_min_i32_e32 v1, s13, v0
	v_mul_lo_u32 v1, v1, s31
	v_cmp_lt_i32_e32 vcc, -1, v0
	v_mov_b32_e32 v111, 0
	s_mov_b32 s18, 0
	v_cndmask_b32_e32 v1, 0, v1, vcc
	v_add_u32_e32 v1, v1, v98
	global_load_dwordx4 v[76:79], v1, s[6:7] offset:768
	global_load_dwordx4 v[72:75], v1, s[6:7] offset:832
	v_add_u32_e32 v1, 16, v0
	v_min_i32_e32 v1, s13, v1
	v_mul_lo_u32 v1, v1, s31
	v_cmp_lt_i32_e32 vcc, s55, v0
	v_mov_b32_e32 v109, 0xf149f2ca
	s_mov_b32 s16, -11
	v_cndmask_b32_e32 v0, 0, v1, vcc
	v_add_u32_e32 v0, v0, v98
	global_load_dwordx4 v[68:71], v0, s[6:7] offset:768
	global_load_dwordx4 v[64:67], v0, s[6:7] offset:832
	v_add_u32_e32 v0, s12, v103
	v_min_i32_e32 v1, s13, v0
	v_add_u32_e32 v2, 8, v0
	v_mul_lo_u32 v1, v1, s31
	v_cmp_lt_i32_e32 vcc, -1, v0
	v_min_i32_e32 v2, s13, v2
	v_mul_lo_u32 v2, v2, s31
	v_cndmask_b32_e32 v1, 0, v1, vcc
	v_cmp_lt_i32_e32 vcc, -9, v0
	v_or_b32_e32 v1, v1, v104
	v_mov_b32_e32 v12, 0
	v_cndmask_b32_e32 v2, 0, v2, vcc
	v_or_b32_e32 v2, v2, v104
	global_load_dwordx4 v[84:87], v1, s[6:7] offset:1536
	global_load_dwordx4 v[80:83], v2, s[6:7] offset:1536
	v_add_u32_e32 v1, 16, v0
	v_min_i32_e32 v1, s13, v1
	v_add_u32_e32 v2, 24, v0
	v_mul_lo_u32 v1, v1, s31
	v_cmp_lt_i32_e32 vcc, s55, v0
	v_min_i32_e32 v2, s13, v2
	v_mul_lo_u32 v2, v2, s31
	v_cndmask_b32_e32 v1, 0, v1, vcc
	v_cmp_lt_i32_e32 vcc, s96, v0
	v_or_b32_e32 v1, v1, v104
	v_mov_b32_e32 v13, v111
	v_cndmask_b32_e32 v0, 0, v2, vcc
	v_or_b32_e32 v0, v0, v104
	global_load_dwordx4 v[92:95], v1, s[6:7] offset:1536
	global_load_dwordx4 v[88:91], v0, s[6:7] offset:1536
	v_mov_b32_e32 v14, v111
	v_mov_b32_e32 v15, v111
	v_mov_b32_e32 v8, 0
	v_mov_b32_e32 v9, v111
	v_mov_b32_e32 v10, v111
	v_mov_b32_e32 v11, v111
	v_mov_b32_e32 v4, v111
	v_mov_b32_e32 v5, v111
	v_mov_b32_e32 v6, v111
	v_mov_b32_e32 v7, v111
	v_mov_b32_e32 v0, v111
	v_mov_b32_e32 v1, v111
	v_mov_b32_e32 v2, v111
	v_mov_b32_e32 v3, v111
	v_mov_b32_e32 v32, v111
	v_mov_b32_e32 v33, v111
	v_mov_b32_e32 v34, v111
	v_mov_b32_e32 v35, v111
	s_add_i32 s20, s16, 11

.Lattp_629:
	s_lshl_b32 s20, -1, s13
	s_andn2_b32 s22, s10, s20
	s_lshr_b32 s20, s15, s13
	s_lshl_b32 s21, s21, 5
	s_add_i32 s20, s20, s21
	s_lshr_b32 s18, s14, s13
	s_sub_i32 s23, s20, 64
	v_add_u32_e32 v116, s23, v49
	s_add_i32 s18, s18, -1
	v_min_i32_e32 v114, s18, v116
	v_cmp_lt_i32_e32 vcc, -1, v116
	v_add_u32_e32 v138, s23, v103
	v_min_i32_e32 v130, s18, v138
	v_cndmask_b32_e32 v114, 0, v114, vcc
	v_lshlrev_b32_e32 v114, s13, v114
	v_add_u32_e32 v114, s22, v114
	v_mad_u64_u32 v[114:115], s[20:21], v114, s31, v[98:99]
	global_load_dwordx4 v[122:125], v114, s[6:7] offset:768
	global_load_dwordx4 v[126:129], v114, s[6:7] offset:832
	v_add_u32_e32 v114, 16, v116
	v_min_i32_e32 v115, s18, v114
	v_cmp_lt_i32_e32 vcc, -1, v114
	v_add_u32_e32 v131, 8, v138
	v_min_i32_e32 v131, s18, v131
	v_cndmask_b32_e32 v114, 0, v115, vcc
	v_cmp_lt_i32_e32 vcc, -1, v138
	v_add_u32_e32 v139, 16, v138
	v_min_i32_e32 v139, s18, v139
	v_cndmask_b32_e32 v130, 0, v130, vcc
	v_cmp_lt_i32_e32 vcc, -9, v138
	v_add_u32_e32 v140, 24, v138
	v_min_i32_e32 v140, s18, v140
	v_cndmask_b32_e32 v131, 0, v131, vcc
	v_cmp_lt_i32_e32 vcc, s55, v138
	v_lshlrev_b32_e32 v130, s13, v130
	v_lshlrev_b32_e32 v131, s13, v131
	v_cndmask_b32_e32 v139, 0, v139, vcc
	v_cmp_lt_i32_e32 vcc, s96, v138
	v_lshlrev_b32_e32 v139, s13, v139
	v_lshlrev_b32_e32 v114, s13, v114
	v_cndmask_b32_e32 v138, 0, v140, vcc
	v_lshlrev_b32_e32 v138, s13, v138
	v_add_u32_e32 v130, s22, v130
	v_add_u32_e32 v131, s22, v131
	v_add_u32_e32 v139, s22, v139
	v_add_u32_e32 v138, s22, v138
	v_add_u32_e32 v114, s22, v114
	v_mul_lo_u32 v130, v130, s31
	v_mul_lo_u32 v131, v131, s31
	v_mul_lo_u32 v139, v139, s31
	v_mul_lo_u32 v138, v138, s31
	v_mad_u64_u32 v[118:119], s[20:21], v114, s31, v[98:99]
	v_or_b32_e32 v130, v130, v104
	v_or_b32_e32 v134, v131, v104
	v_or_b32_e32 v139, v139, v104
	v_or_b32_e32 v142, v138, v104
	global_load_dwordx4 v[114:117], v118, s[6:7] offset:768
	s_nop 0
	global_load_dwordx4 v[118:121], v118, s[6:7] offset:832
	s_nop 0
	global_load_dwordx4 v[130:133], v130, s[6:7] offset:1536
	s_nop 0
	global_load_dwordx4 v[134:137], v134, s[6:7] offset:1536
	s_nop 0
	global_load_dwordx4 v[138:141], v139, s[6:7] offset:1536
	s_nop 0
	global_load_dwordx4 v[142:145], v142, s[6:7] offset:1536
	s_mov_b32 s18, 0

.LBB0_626:
	s_add_i32 s17, s18, 1
	s_mov_b32 s13, 0
	s_add_i32 s21, s17, 1
	s_cmp_lt_u32 s20, 10
	s_cbranch_scc1 .LBB0_629
	s_mov_b32 s13, 2
	s_add_i32 s21, s16, 1
	s_cmp_lt_u32 s20, 16
	s_cbranch_scc1 .LBB0_629
	s_sub_i32 s21, s18, 16
	s_mov_b32 s13, 4
.LBB0_629:
	s_lshl_b32 s20, -1, s13
	s_andn2_b32 s22, s10, s20
	s_lshr_b32 s20, s15, s13
	s_lshl_b32 s21, s21, 5
	s_add_i32 s20, s20, s21
	s_lshr_b32 s18, s14, s13
	s_sub_i32 s23, s20, 64
	v_add_u32_e32 v26, s23, v49
	s_add_i32 s18, s18, -1
	v_min_i32_e32 v24, s18, v26
	v_cmp_lt_i32_e32 vcc, -1, v26
	v_add_u32_e32 v56, s23, v103
	v_min_i32_e32 v44, s18, v56
	v_cndmask_b32_e32 v24, 0, v24, vcc
	v_lshlrev_b32_e32 v24, s13, v24
	v_add_u32_e32 v24, s22, v24
	v_mad_u64_u32 v[24:25], s[20:21], v24, s31, v[98:99]
	global_load_dwordx4 v[36:39], v24, s[6:7] offset:768
	global_load_dwordx4 v[40:43], v24, s[6:7] offset:832
	v_add_u32_e32 v24, 16, v26
	v_min_i32_e32 v25, s18, v24
	v_cmp_lt_i32_e32 vcc, -1, v24
	v_add_u32_e32 v45, 8, v56
	v_min_i32_e32 v45, s18, v45
	v_cndmask_b32_e32 v24, 0, v25, vcc
	v_cmp_lt_i32_e32 vcc, -1, v56
	v_add_u32_e32 v57, 16, v56
	v_min_i32_e32 v57, s18, v57
	v_cndmask_b32_e32 v44, 0, v44, vcc
	v_cmp_lt_i32_e32 vcc, -9, v56
	v_add_u32_e32 v58, 24, v56
	v_min_i32_e32 v58, s18, v58
	v_cndmask_b32_e32 v45, 0, v45, vcc
	v_cmp_lt_i32_e32 vcc, s55, v56
	v_lshlrev_b32_e32 v44, s13, v44
	v_lshlrev_b32_e32 v45, s13, v45
	v_cndmask_b32_e32 v57, 0, v57, vcc
	v_cmp_lt_i32_e32 vcc, s96, v56
	v_lshlrev_b32_e32 v57, s13, v57
	v_lshlrev_b32_e32 v24, s13, v24
	v_cndmask_b32_e32 v56, 0, v58, vcc
	v_lshlrev_b32_e32 v56, s13, v56
	v_add_u32_e32 v44, s22, v44
	v_add_u32_e32 v45, s22, v45
	v_add_u32_e32 v57, s22, v57
	v_add_u32_e32 v56, s22, v56
	v_add_u32_e32 v24, s22, v24
	v_mul_lo_u32 v44, v44, s31
	v_mul_lo_u32 v45, v45, s31
	v_mul_lo_u32 v57, v57, s31
	v_mul_lo_u32 v56, v56, s31
	v_mad_u64_u32 v[28:29], s[20:21], v24, s31, v[98:99]
	v_or_b32_e32 v44, v44, v104
	v_or_b32_e32 v52, v45, v104
	v_or_b32_e32 v57, v57, v104
	v_or_b32_e32 v60, v56, v104
	global_load_dwordx4 v[24:27], v28, s[6:7] offset:768
	s_nop 0
	global_load_dwordx4 v[28:31], v28, s[6:7] offset:832
	s_nop 0
	global_load_dwordx4 v[44:47], v44, s[6:7] offset:1536
	s_nop 0
	global_load_dwordx4 v[52:55], v52, s[6:7] offset:1536
	s_nop 0
	global_load_dwordx4 v[56:59], v57, s[6:7] offset:1536
	s_nop 0
	global_load_dwordx4 v[60:63], v60, s[6:7] offset:1536
	s_lshr_b32 s13, s15, s12
	v_lshrrev_b32_e32 v112, s12, v110
	s_lshl_b32 s18, s19, 5
	s_lshr_b32 s19, s14, s12
	s_lshr_b32 s12, s12, 1
	s_waitcnt vmcnt(19)
	ds_write_b128 v108, v[84:87] offset:16384
	s_waitcnt vmcnt(18)
	ds_write_b128 v108, v[80:83] offset:17536
	s_waitcnt vmcnt(17)
	ds_write_b128 v108, v[92:95] offset:18688
	s_waitcnt vmcnt(16)
	ds_write_b128 v108, v[88:91] offset:19840
	v_add_u32_e32 v80, s13, v105
	v_sub_u32_e32 v81, v80, v112
	s_mul_i32 s12, s12, 6
	v_add_u32_e32 v81, s18, v81
	s_add_i32 s12, s12, s1
	s_mulk_i32 s12, 0x210
	v_add_u32_e32 v83, 1, v81
	v_add_u32_e32 v85, 2, v81
	v_add_u32_e32 v87, 3, v81
	v_add_u32_e32 v89, 16, v81
	v_add_u32_e32 v91, 17, v81
	v_add_u32_e32 v93, 18, v81
	v_add_u32_e32 v95, 19, v81
	s_add_i32 s12, s12, 0
	v_med3_i32 v82, v81, s30, 64
	v_med3_i32 v84, v83, s30, 64
	v_med3_i32 v86, v85, s30, 64
	v_med3_i32 v88, v87, s30, 64
	v_med3_i32 v90, v89, s30, 64
	v_med3_i32 v92, v91, s30, 64
	v_med3_i32 v94, v93, s30, 64
	v_med3_i32 v113, v95, s30, 64
	v_lshl_add_u32 v82, v82, 2, s12
	v_lshl_add_u32 v84, v84, 2, s12
	v_lshl_add_u32 v86, v86, 2, s12
	v_lshl_add_u32 v88, v88, 2, s12
	v_lshl_add_u32 v90, v90, 2, s12
	v_lshl_add_u32 v92, v92, 2, s12
	v_lshl_add_u32 v94, v94, 2, s12
	v_lshl_add_u32 v113, v113, 2, s12
	ds_read_b32 v82, v82 offset:256
	ds_read_b32 v84, v84 offset:256
	ds_read_b32 v86, v86 offset:256
	ds_read_b32 v88, v88 offset:256
	ds_read_b32 v90, v90 offset:256
	ds_read_b32 v92, v92 offset:256
	ds_read_b32 v94, v94 offset:256
	ds_read_b32 v113, v113 offset:256
	s_waitcnt lgkmcnt(7)
	s_waitcnt lgkmcnt(6)
	s_waitcnt lgkmcnt(5)
	s_waitcnt lgkmcnt(4)
	s_waitcnt lgkmcnt(3)
	s_waitcnt lgkmcnt(2)
	s_waitcnt lgkmcnt(1)
	s_waitcnt lgkmcnt(0)
	s_setprio 1
	v_mfma_f32_16x16x32_bf16 v[76:79], v[76:79], v[16:19], 0
	v_mfma_f32_16x16x32_bf16 v[72:75], v[72:75], v[20:23], v[76:79]
	s_setprio 0
	s_nop 5
	v_add_u32_e32 v76, s18, v80
	v_add_u32_e32 v77, 64, v81
	v_cmp_gt_u32_e32 vcc, s97, v77
	v_cmp_gt_u32_e64 s[38:39], s19, v76
	v_fmac_f32_e32 v82, 0x3e000000, v72
	s_and_b64 vcc, vcc, s[38:39]
	v_add_u32_e32 v76, v83, v112
	v_add_u32_e32 v77, 0x41, v81
	v_cndmask_b32_e32 v72, v233, v82, vcc
	v_cmp_gt_u32_e32 vcc, s97, v77
	v_cmp_gt_u32_e64 s[38:39], s19, v76
	v_fmac_f32_e32 v84, 0x3e000000, v73
	s_and_b64 vcc, vcc, s[38:39]
	v_add_u32_e32 v76, v85, v112
	v_add_u32_e32 v77, 0x42, v81
	v_cndmask_b32_e32 v73, v233, v84, vcc
	v_cmp_gt_u32_e32 vcc, s97, v77
	v_cmp_gt_u32_e64 s[38:39], s19, v76
	v_fmac_f32_e32 v86, 0x3e000000, v74
	s_and_b64 vcc, vcc, s[38:39]
	v_add_u32_e32 v76, v87, v112
	v_add_u32_e32 v77, 0x43, v81
	v_cndmask_b32_e32 v74, v233, v86, vcc
	v_cmp_gt_u32_e32 vcc, s97, v77
	v_cmp_gt_u32_e64 s[38:39], s19, v76
	v_fmac_f32_e32 v88, 0x3e000000, v75
	s_and_b64 vcc, vcc, s[38:39]
	v_cndmask_b32_e32 v75, v233, v88, vcc
	s_setprio 1
	v_mfma_f32_16x16x32_bf16 v[68:71], v[68:71], v[16:19], 0
	v_mfma_f32_16x16x32_bf16 v[64:67], v[64:67], v[20:23], v[68:71]
	s_setprio 0
	s_nop 5
	v_add_u32_e32 v68, v89, v112
	v_add_u32_e32 v69, 0x50, v81
	v_cmp_gt_u32_e32 vcc, s97, v69
	v_cmp_gt_u32_e64 s[38:39], s19, v68
	v_fmac_f32_e32 v90, 0x3e000000, v64
	s_and_b64 vcc, vcc, s[38:39]
	v_add_u32_e32 v68, v91, v112
	v_add_u32_e32 v69, 0x51, v81
	v_cndmask_b32_e32 v64, v233, v90, vcc
	v_cmp_gt_u32_e32 vcc, s97, v69
	v_cmp_gt_u32_e64 s[38:39], s19, v68
	v_fmac_f32_e32 v92, 0x3e000000, v65
	s_and_b64 vcc, vcc, s[38:39]
	v_add_u32_e32 v68, v93, v112
	v_add_u32_e32 v69, 0x52, v81
	v_cndmask_b32_e32 v65, v233, v92, vcc
	v_cmp_gt_u32_e32 vcc, s97, v69
	v_cmp_gt_u32_e64 s[38:39], s19, v68
	v_fmac_f32_e32 v94, 0x3e000000, v66
	s_and_b64 vcc, vcc, s[38:39]
	v_add_u32_e32 v68, v95, v112
	v_add_u32_e32 v69, 0x53, v81
	v_cndmask_b32_e32 v66, v233, v94, vcc
	v_cmp_gt_u32_e32 vcc, s97, v69
	v_cmp_gt_u32_e64 s[38:39], s19, v68
	v_max_f32_e32 v68, v72, v73
	v_fmac_f32_e32 v113, 0x3e000000, v67
	s_and_b64 vcc, vcc, s[38:39]
	v_max3_f32 v68, v68, v74, v75
	v_cndmask_b32_e32 v67, v233, v113, vcc
	v_max3_f32 v68, v68, v64, v65
	v_max3_f32 v68, v68, v66, v67
	v_add_f32_e32 v69, 0x41000000, v109
	v_cmp_gt_f32_e32 vcc, v68, v69
	s_cmp_lg_u64 vcc, 0
	s_cselect_b64 s[12:13], -1, 0
	s_cbranch_vccz .LBB0_631
	v_and_b32_e32 v70, 64, v234
	v_xor_b32_e32 v69, 16, v234
	v_add_u32_e32 v70, 64, v70
	v_cmp_lt_i32_e32 vcc, v69, v70
	s_nop 1
	v_cndmask_b32_e32 v69, v234, v69, vcc
	v_lshlrev_b32_e32 v69, 2, v69
	ds_bpermute_b32 v69, v69, v68
	v_max_f32_e32 v68, v68, v68
	s_waitcnt lgkmcnt(0)
	v_max_f32_e32 v69, v69, v69
	v_max_f32_e32 v68, v68, v69
	v_xor_b32_e32 v69, 32, v234
	v_cmp_lt_i32_e32 vcc, v69, v70
	s_nop 1
	v_cndmask_b32_e32 v69, v234, v69, vcc
	v_lshlrev_b32_e32 v69, 2, v69
	ds_bpermute_b32 v69, v69, v68
	s_waitcnt lgkmcnt(0)
	v_max3_f32 v69, v109, v68, v69
	v_sub_f32_e32 v68, v109, v69
	v_mul_f32_e32 v68, 0x3fb8aa3b, v68
	v_exp_f32_e32 v68, v68
	v_mov_b32_e32 v109, v69
	s_branch .LBB0_632

.LBB0_634:
	v_add_f32_e32 v12, 0, v69
	v_add_f32_e32 v12, v70, v12
	v_add_f32_e32 v12, v71, v12
	v_add_f32_e32 v12, v72, v12
	v_add_f32_e32 v12, v73, v12
	v_add_f32_e32 v12, v74, v12
	v_add_f32_e32 v12, v75, v12
	v_add_f32_e32 v112, v76, v12
	ds_read_b64_tr_b16 v[12:13], v106 offset:16384
	ds_read_b64_tr_b16 v[14:15], v107 offset:16384
	v_fmac_f32_e32 v112, v111, v68
	s_setprio 1
	s_waitcnt lgkmcnt(0)
	v_mfma_f32_16x16x32_bf16 v[8:11], v[12:15], v[64:67], v[8:11]
	s_setprio 0
	ds_read_b64_tr_b16 v[12:13], v106 offset:16416
	ds_read_b64_tr_b16 v[14:15], v107 offset:16416
	s_setprio 1
	s_waitcnt lgkmcnt(0)
	v_mfma_f32_16x16x32_bf16 v[4:7], v[12:15], v[64:67], v[4:7]
	s_setprio 0
	ds_read_b64_tr_b16 v[12:13], v106 offset:16448
	ds_read_b64_tr_b16 v[14:15], v107 offset:16448
	s_setprio 1
	s_waitcnt lgkmcnt(0)
	v_mfma_f32_16x16x32_bf16 v[0:3], v[12:15], v[64:67], v[0:3]
	s_setprio 0
	ds_read_b64_tr_b16 v[12:13], v106 offset:16480
	ds_read_b64_tr_b16 v[14:15], v107 offset:16480
	s_setprio 1
	s_waitcnt lgkmcnt(0)
	v_mfma_f32_16x16x32_bf16 v[12:15], v[12:15], v[64:67], v[32:35]
	s_setprio 0
	s_add_i32 s16, s16, 1
	s_cmp_eq_u32 s16, 11
	s_cbranch_scc1 .LBB0_636
	s_waitcnt vmcnt(12)
	v_mov_b64_e32 v[66:67], v[120:121]
	v_mov_b64_e32 v[70:71], v[116:117]
	v_mov_b64_e32 v[74:75], v[128:129]
	v_mov_b64_e32 v[78:79], v[124:125]
	s_waitcnt vmcnt(8)
	v_mov_b64_e32 v[90:91], v[144:145]
	v_mov_b64_e32 v[94:95], v[140:141]
	v_mov_b64_e32 v[82:83], v[136:137]
	v_mov_b64_e32 v[86:87], v[132:133]
	v_mov_b64_e32 v[64:65], v[118:119]
	v_mov_b64_e32 v[68:69], v[114:115]
	v_mov_b64_e32 v[72:73], v[126:127]
	v_mov_b64_e32 v[76:77], v[122:123]
	v_mov_b64_e32 v[88:89], v[142:143]
	v_mov_b64_e32 v[92:93], v[138:139]
	v_mov_b64_e32 v[80:81], v[134:135]
	v_mov_b64_e32 v[84:85], v[130:131]
	v_mov_b32_e32 v111, v112
	s_mov_b32 s18, s17
	v_mov_b32_e32 v32, v12
	v_mov_b32_e32 v33, v13
	v_mov_b32_e32 v34, v14
	v_mov_b32_e32 v35, v15

.Lattb_629:
	s_cmp_eq_u32 s20, 21
	s_cbranch_scc1 .Lattb_nopf
	s_lshl_b32 s20, -1, s13
	s_andn2_b32 s22, s10, s20
	s_lshr_b32 s20, s15, s13
	s_lshl_b32 s21, s21, 5
	s_add_i32 s20, s20, s21
	s_lshr_b32 s18, s14, s13
	s_sub_i32 s23, s20, 64
	v_add_u32_e32 v116, s23, v49
	s_add_i32 s18, s18, -1
	v_min_i32_e32 v114, s18, v116
	v_cmp_lt_i32_e32 vcc, -1, v116
	v_add_u32_e32 v138, s23, v103
	v_min_i32_e32 v130, s18, v138
	v_cndmask_b32_e32 v114, 0, v114, vcc
	v_lshlrev_b32_e32 v114, s13, v114
	v_add_u32_e32 v114, s22, v114
	v_mad_u64_u32 v[114:115], s[20:21], v114, s31, v[98:99]
	global_load_dwordx4 v[122:125], v114, s[6:7] offset:768
	global_load_dwordx4 v[126:129], v114, s[6:7] offset:832
	v_add_u32_e32 v114, 16, v116
	v_min_i32_e32 v115, s18, v114
	v_cmp_lt_i32_e32 vcc, -1, v114
	v_add_u32_e32 v131, 8, v138
	v_min_i32_e32 v131, s18, v131
	v_cndmask_b32_e32 v114, 0, v115, vcc
	v_cmp_lt_i32_e32 vcc, -1, v138
	v_add_u32_e32 v139, 16, v138
	v_min_i32_e32 v139, s18, v139
	v_cndmask_b32_e32 v130, 0, v130, vcc
	v_cmp_lt_i32_e32 vcc, -9, v138
	v_add_u32_e32 v140, 24, v138
	v_min_i32_e32 v140, s18, v140
	v_cndmask_b32_e32 v131, 0, v131, vcc
	v_cmp_lt_i32_e32 vcc, s55, v138
	v_lshlrev_b32_e32 v130, s13, v130
	v_lshlrev_b32_e32 v131, s13, v131
	v_cndmask_b32_e32 v139, 0, v139, vcc
	v_cmp_lt_i32_e32 vcc, s96, v138
	v_lshlrev_b32_e32 v139, s13, v139
	v_lshlrev_b32_e32 v114, s13, v114
	v_cndmask_b32_e32 v138, 0, v140, vcc
	v_lshlrev_b32_e32 v138, s13, v138
	v_add_u32_e32 v130, s22, v130
	v_add_u32_e32 v131, s22, v131
	v_add_u32_e32 v139, s22, v139
	v_add_u32_e32 v138, s22, v138
	v_add_u32_e32 v114, s22, v114
	v_mul_lo_u32 v130, v130, s31
	v_mul_lo_u32 v131, v131, s31
	v_mul_lo_u32 v139, v139, s31
	v_mul_lo_u32 v138, v138, s31
	v_mad_u64_u32 v[118:119], s[20:21], v114, s31, v[98:99]
	v_or_b32_e32 v130, v130, v104
	v_or_b32_e32 v134, v131, v104
	v_or_b32_e32 v139, v139, v104
	v_or_b32_e32 v142, v138, v104
	global_load_dwordx4 v[114:117], v118, s[6:7] offset:768
	s_nop 0
	global_load_dwordx4 v[118:121], v118, s[6:7] offset:832
	s_nop 0
	global_load_dwordx4 v[130:133], v130, s[6:7] offset:1536
	s_nop 0
	global_load_dwordx4 v[134:137], v134, s[6:7] offset:1536
	s_nop 0
	global_load_dwordx4 v[138:141], v139, s[6:7] offset:1536
	s_nop 0
	global_load_dwordx4 v[142:145], v142, s[6:7] offset:1536
.Lattb_nopf:
	s_lshr_b32 s13, s15, s12
	v_lshrrev_b32_e32 v112, s12, v110
	s_lshl_b32 s18, s19, 5
	s_lshr_b32 s19, s14, s12
	s_lshr_b32 s12, s12, 1
	s_waitcnt vmcnt(19)
	ds_write_b128 v108, v[84:87] offset:16384
	s_waitcnt vmcnt(18)
	ds_write_b128 v108, v[80:83] offset:17536
	s_waitcnt vmcnt(17)
	ds_write_b128 v108, v[92:95] offset:18688
	s_waitcnt vmcnt(16)
	ds_write_b128 v108, v[88:91] offset:19840
	v_add_u32_e32 v80, s13, v105
	v_sub_u32_e32 v81, v80, v112
	s_mul_i32 s12, s12, 6
	v_add_u32_e32 v81, s18, v81
	s_add_i32 s12, s12, s1
	s_mulk_i32 s12, 0x210
	v_add_u32_e32 v83, 1, v81
	v_add_u32_e32 v85, 2, v81
	v_add_u32_e32 v87, 3, v81
	v_add_u32_e32 v89, 16, v81
	v_add_u32_e32 v91, 17, v81
	v_add_u32_e32 v93, 18, v81
	v_add_u32_e32 v95, 19, v81
	s_add_i32 s12, s12, 0
	v_med3_i32 v82, v81, s30, 64
	v_med3_i32 v84, v83, s30, 64
	v_med3_i32 v86, v85, s30, 64
	v_med3_i32 v88, v87, s30, 64
	v_med3_i32 v90, v89, s30, 64
	v_med3_i32 v92, v91, s30, 64
	v_med3_i32 v94, v93, s30, 64
	v_med3_i32 v113, v95, s30, 64
	v_lshl_add_u32 v82, v82, 2, s12
	v_lshl_add_u32 v84, v84, 2, s12
	v_lshl_add_u32 v86, v86, 2, s12
	v_lshl_add_u32 v88, v88, 2, s12
	v_lshl_add_u32 v90, v90, 2, s12
	v_lshl_add_u32 v92, v92, 2, s12
	v_lshl_add_u32 v94, v94, 2, s12
	v_lshl_add_u32 v113, v113, 2, s12
	ds_read_b32 v82, v82 offset:256
	ds_read_b32 v84, v84 offset:256
	ds_read_b32 v86, v86 offset:256
	ds_read_b32 v88, v88 offset:256
	ds_read_b32 v90, v90 offset:256
	ds_read_b32 v92, v92 offset:256
	ds_read_b32 v94, v94 offset:256
	ds_read_b32 v113, v113 offset:256
	s_waitcnt lgkmcnt(7)
	s_waitcnt lgkmcnt(6)
	s_waitcnt lgkmcnt(5)
	s_waitcnt lgkmcnt(4)
	s_waitcnt lgkmcnt(3)
	s_waitcnt lgkmcnt(2)
	s_waitcnt lgkmcnt(1)
	s_waitcnt lgkmcnt(0)
	s_setprio 1
	v_mfma_f32_16x16x32_bf16 v[76:79], v[76:79], v[16:19], 0
	v_mfma_f32_16x16x32_bf16 v[72:75], v[72:75], v[20:23], v[76:79]
	s_setprio 0
	s_nop 5
	v_add_u32_e32 v76, s18, v80
	v_add_u32_e32 v77, 64, v81
	v_cmp_gt_u32_e32 vcc, s97, v77
	v_cmp_gt_u32_e64 s[38:39], s19, v76
	v_fmac_f32_e32 v82, 0x3e000000, v72
	s_and_b64 vcc, vcc, s[38:39]
	v_add_u32_e32 v76, v83, v112
	v_add_u32_e32 v77, 0x41, v81
	v_cndmask_b32_e32 v72, v233, v82, vcc
	v_cmp_gt_u32_e32 vcc, s97, v77
	v_cmp_gt_u32_e64 s[38:39], s19, v76
	v_fmac_f32_e32 v84, 0x3e000000, v73
	s_and_b64 vcc, vcc, s[38:39]
	v_add_u32_e32 v76, v85, v112
	v_add_u32_e32 v77, 0x42, v81
	v_cndmask_b32_e32 v73, v233, v84, vcc
	v_cmp_gt_u32_e32 vcc, s97, v77
	v_cmp_gt_u32_e64 s[38:39], s19, v76
	v_fmac_f32_e32 v86, 0x3e000000, v74
	s_and_b64 vcc, vcc, s[38:39]
	v_add_u32_e32 v76, v87, v112
	v_add_u32_e32 v77, 0x43, v81
	v_cndmask_b32_e32 v74, v233, v86, vcc
	v_cmp_gt_u32_e32 vcc, s97, v77
	v_cmp_gt_u32_e64 s[38:39], s19, v76
	v_fmac_f32_e32 v88, 0x3e000000, v75
	s_and_b64 vcc, vcc, s[38:39]
	v_cndmask_b32_e32 v75, v233, v88, vcc
	s_setprio 1
	v_mfma_f32_16x16x32_bf16 v[68:71], v[68:71], v[16:19], 0
	v_mfma_f32_16x16x32_bf16 v[64:67], v[64:67], v[20:23], v[68:71]
	s_setprio 0
	s_nop 5
	v_add_u32_e32 v68, v89, v112
	v_add_u32_e32 v69, 0x50, v81
	v_cmp_gt_u32_e32 vcc, s97, v69
	v_cmp_gt_u32_e64 s[38:39], s19, v68
	v_fmac_f32_e32 v90, 0x3e000000, v64
	s_and_b64 vcc, vcc, s[38:39]
	v_add_u32_e32 v68, v91, v112
	v_add_u32_e32 v69, 0x51, v81
	v_cndmask_b32_e32 v64, v233, v90, vcc
	v_cmp_gt_u32_e32 vcc, s97, v69
	v_cmp_gt_u32_e64 s[38:39], s19, v68
	v_fmac_f32_e32 v92, 0x3e000000, v65
	s_and_b64 vcc, vcc, s[38:39]
	v_add_u32_e32 v68, v93, v112
	v_add_u32_e32 v69, 0x52, v81
	v_cndmask_b32_e32 v65, v233, v92, vcc
	v_cmp_gt_u32_e32 vcc, s97, v69
	v_cmp_gt_u32_e64 s[38:39], s19, v68
	v_fmac_f32_e32 v94, 0x3e000000, v66
	s_and_b64 vcc, vcc, s[38:39]
	v_add_u32_e32 v68, v95, v112
	v_add_u32_e32 v69, 0x53, v81
	v_cndmask_b32_e32 v66, v233, v94, vcc
	v_cmp_gt_u32_e32 vcc, s97, v69
	v_cmp_gt_u32_e64 s[38:39], s19, v68
	v_max_f32_e32 v68, v72, v73
	v_fmac_f32_e32 v113, 0x3e000000, v67
	s_and_b64 vcc, vcc, s[38:39]
	v_max3_f32 v68, v68, v74, v75
	v_cndmask_b32_e32 v67, v233, v113, vcc
	v_max3_f32 v68, v68, v64, v65
	v_max3_f32 v68, v68, v66, v67
	v_add_f32_e32 v69, 0x41000000, v109
	v_cmp_gt_f32_e32 vcc, v68, v69
	s_cmp_lg_u64 vcc, 0
	s_cselect_b64 s[12:13], -1, 0
	s_cbranch_vccz .Lattb_631
	v_and_b32_e32 v70, 64, v234
	v_xor_b32_e32 v69, 16, v234
	v_add_u32_e32 v70, 64, v70
	v_cmp_lt_i32_e32 vcc, v69, v70
	s_nop 1
	v_cndmask_b32_e32 v69, v234, v69, vcc
	v_lshlrev_b32_e32 v69, 2, v69
	ds_bpermute_b32 v69, v69, v68
	v_max_f32_e32 v68, v68, v68
	s_waitcnt lgkmcnt(0)
	v_max_f32_e32 v69, v69, v69
	v_max_f32_e32 v68, v68, v69
	v_xor_b32_e32 v69, 32, v234
	v_cmp_lt_i32_e32 vcc, v69, v70
	s_nop 1
	v_cndmask_b32_e32 v69, v234, v69, vcc
	v_lshlrev_b32_e32 v69, 2, v69
	ds_bpermute_b32 v69, v69, v68
	s_waitcnt lgkmcnt(0)
	v_max3_f32 v69, v109, v68, v69
	v_sub_f32_e32 v68, v109, v69
	v_mul_f32_e32 v68, 0x3fb8aa3b, v68
	v_exp_f32_e32 v68, v68
	v_mov_b32_e32 v109, v69
	s_branch .Lattb_632

.Lattb_634:
	v_add_f32_e32 v12, 0, v69
	v_add_f32_e32 v12, v70, v12
	v_add_f32_e32 v12, v71, v12
	v_add_f32_e32 v12, v72, v12
	v_add_f32_e32 v12, v73, v12
	v_add_f32_e32 v12, v74, v12
	v_add_f32_e32 v12, v75, v12
	v_add_f32_e32 v112, v76, v12
	ds_read_b64_tr_b16 v[12:13], v106 offset:16384
	ds_read_b64_tr_b16 v[14:15], v107 offset:16384
	v_fmac_f32_e32 v112, v111, v68
	s_setprio 1
	s_waitcnt lgkmcnt(0)
	v_mfma_f32_16x16x32_bf16 v[8:11], v[12:15], v[64:67], v[8:11]
	s_setprio 0
	ds_read_b64_tr_b16 v[12:13], v106 offset:16416
	ds_read_b64_tr_b16 v[14:15], v107 offset:16416
	s_setprio 1
	s_waitcnt lgkmcnt(0)
	v_mfma_f32_16x16x32_bf16 v[4:7], v[12:15], v[64:67], v[4:7]
	s_setprio 0
	ds_read_b64_tr_b16 v[12:13], v106 offset:16448
	ds_read_b64_tr_b16 v[14:15], v107 offset:16448
	s_setprio 1
	s_waitcnt lgkmcnt(0)
	v_mfma_f32_16x16x32_bf16 v[0:3], v[12:15], v[64:67], v[0:3]
	s_setprio 0
	ds_read_b64_tr_b16 v[12:13], v106 offset:16480
	ds_read_b64_tr_b16 v[14:15], v107 offset:16480
	s_setprio 1
	s_waitcnt lgkmcnt(0)
	v_mfma_f32_16x16x32_bf16 v[12:15], v[12:15], v[64:67], v[32:35]
	s_setprio 0
	s_add_i32 s16, s16, 1
	s_cmp_eq_u32 s16, 11
	s_cbranch_scc1 .LBB0_636
	s_waitcnt vmcnt(12)
	v_mov_b64_e32 v[66:67], v[30:31]
	v_mov_b64_e32 v[70:71], v[26:27]
	v_mov_b64_e32 v[74:75], v[42:43]
	v_mov_b64_e32 v[78:79], v[38:39]
	s_waitcnt vmcnt(8)
	v_mov_b64_e32 v[90:91], v[62:63]
	v_mov_b64_e32 v[94:95], v[58:59]
	v_mov_b64_e32 v[82:83], v[54:55]
	v_mov_b64_e32 v[86:87], v[46:47]
	v_mov_b64_e32 v[64:65], v[28:29]
	v_mov_b64_e32 v[68:69], v[24:25]
	v_mov_b64_e32 v[72:73], v[40:41]
	v_mov_b64_e32 v[76:77], v[36:37]
	v_mov_b64_e32 v[88:89], v[60:61]
	v_mov_b64_e32 v[92:93], v[56:57]
	v_mov_b64_e32 v[80:81], v[52:53]
	v_mov_b64_e32 v[84:85], v[44:45]
	v_mov_b32_e32 v111, v112
	s_mov_b32 s18, s17
	v_mov_b32_e32 v32, v12
	v_mov_b32_e32 v33, v13
	v_mov_b32_e32 v34, v14
	v_mov_b32_e32 v35, v15
	s_branch .LBB0_621
